# attention: packed f32 math in softmax (ctx pass v_pk_fma/v_pk_add, local half bias v_pk_fma + v_pk_add sums); same f32 math, half the VALU issue slots
# speedup vs baseline: 1.0066x; 1.0025x over previous
.LBB0_296:
	s_or_b64 exec, exec, s[68:69]
	v_mov_b32_e32 v216, 0x3e38aa3b
	v_mov_b32_e32 v217, 0x3e38aa3b
	s_add_i32 s64, s64, -4
	s_min_u32 s64, s64, 56
	v_sub_u32_e32 v36, s64, v26
	v_lshl_add_u32 v24, v36, 13, v128
	v_add_u32_e32 v25, v24, v126
	s_waitcnt lgkmcnt(0)
	s_barrier
	v_add_u32_e32 v26, v24, v127
	ds_read_b128 v[30:33], v25
	ds_read_b128 v[38:41], v25 offset:512
	ds_read_b128 v[42:45], v26
	ds_read_b128 v[46:49], v26 offset:512
	ds_read_b128 v[50:53], v25 offset:8192
	ds_read_b128 v[54:57], v25 offset:8704
	ds_read_b128 v[58:61], v26 offset:8192
	ds_read_b128 v[62:65], v26 offset:8704
	s_sub_i32 s63, s64, s63
	v_lshl_add_u32 v24, s63, 8, v129
	v_add_u32_e32 v235, 0x77c, v24
	v_add_u32_e32 v236, 0xb7c, v24
	s_waitcnt lgkmcnt(7)
	v_mfma_f32_16x16x32_bf16 v[30:33], v[30:33], v[4:7], 0
	ds_read2_b32 v[34:35], v235 offset0:0 offset1:1
	s_waitcnt lgkmcnt(6)
	v_mfma_f32_16x16x32_bf16 v[30:33], v[42:45], v[0:3], v[30:33]
	v_mfma_f32_16x16x32_bf16 v[38:41], v[38:41], v[4:7], 0
	s_waitcnt lgkmcnt(5)
	v_mfma_f32_16x16x32_bf16 v[38:41], v[46:49], v[0:3], v[38:41]
	ds_read2_b32 v[238:239], v235 offset0:2 offset1:3
	ds_read2_b32 v[240:241], v235 offset0:4 offset1:5
	ds_read2_b32 v[242:243], v235 offset0:6 offset1:7
	s_waitcnt lgkmcnt(0)
	s_nop 3
	v_pk_fma_f32 v[34:35], v[30:31], v[216:217], v[34:35]
	v_cndmask_b32_e64 v30, v222, v34, s[6:7]
	v_cndmask_b32_e64 v29, v222, v35, s[8:9]
	v_pk_fma_f32 v[238:239], v[32:33], v[216:217], v[238:239]
	v_cndmask_b32_e64 v32, v222, v238, s[10:11]
	v_cndmask_b32_e64 v31, v222, v239, s[12:13]
	v_pk_fma_f32 v[240:241], v[38:39], v[216:217], v[240:241]
	v_cndmask_b32_e64 v34, v222, v240, s[14:15]
	v_cndmask_b32_e64 v33, v222, v241, s[16:17]
	v_pk_fma_f32 v[242:243], v[40:41], v[216:217], v[242:243]
	v_cndmask_b32_e64 v43, v222, v242, s[18:19]
	v_cndmask_b32_e64 v41, v222, v243, s[20:21]
	ds_read_b128 v[44:47], v25 offset:16384
	ds_read_b128 v[66:69], v25 offset:16896
	ds_read_b128 v[100:103], v26 offset:16384
	ds_read_b128 v[152:155], v26 offset:16896
	v_mfma_f32_16x16x32_bf16 v[48:51], v[50:53], v[4:7], 0
	ds_read2_b32 v[38:39], v235 offset0:64 offset1:65
	v_mfma_f32_16x16x32_bf16 v[48:51], v[58:61], v[0:3], v[48:51]
	v_mfma_f32_16x16x32_bf16 v[52:55], v[54:57], v[4:7], 0
	v_mfma_f32_16x16x32_bf16 v[52:55], v[62:65], v[0:3], v[52:55]
	ds_read2_b32 v[238:239], v235 offset0:66 offset1:67
	ds_read2_b32 v[240:241], v235 offset0:68 offset1:69
	ds_read2_b32 v[242:243], v235 offset0:70 offset1:71
	s_waitcnt lgkmcnt(0)
	s_nop 4
	v_pk_fma_f32 v[38:39], v[48:49], v[216:217], v[38:39]
	v_cndmask_b32_e64 v37, v222, v38, s[6:7]
	v_cndmask_b32_e64 v35, v222, v39, s[8:9]
	v_pk_fma_f32 v[238:239], v[50:51], v[216:217], v[238:239]
	v_cndmask_b32_e64 v39, v222, v238, s[10:11]
	v_cndmask_b32_e64 v38, v222, v239, s[12:13]
	v_pk_fma_f32 v[240:241], v[52:53], v[216:217], v[240:241]
	v_cndmask_b32_e64 v42, v222, v240, s[14:15]
	v_cndmask_b32_e64 v40, v222, v241, s[16:17]
	v_pk_fma_f32 v[242:243], v[54:55], v[216:217], v[242:243]
	v_cndmask_b32_e64 v51, v222, v242, s[18:19]
	v_cndmask_b32_e64 v49, v222, v243, s[20:21]
	ds_read_b128 v[52:55], v25 offset:24576
	ds_read_b128 v[60:63], v25 offset:25088
	ds_read_b128 v[170:173], v26 offset:24576
	ds_read_b128 v[174:177], v26 offset:25088
	v_mfma_f32_16x16x32_bf16 v[44:47], v[44:47], v[4:7], 0
	v_mfma_f32_16x16x32_bf16 v[56:59], v[66:69], v[4:7], 0
	v_mfma_f32_16x16x32_bf16 v[64:67], v[100:103], v[0:3], v[44:47]
	s_nop 4
	ds_read2_b32 v[46:47], v235 offset0:128 offset1:129
	v_mfma_f32_16x16x32_bf16 v[68:71], v[152:155], v[0:3], v[56:59]
	ds_read2_b32 v[238:239], v235 offset0:130 offset1:131
	ds_read2_b32 v[240:241], v235 offset0:132 offset1:133
	ds_read2_b32 v[242:243], v235 offset0:134 offset1:135
	s_waitcnt lgkmcnt(0)
	v_pk_fma_f32 v[46:47], v[64:65], v[216:217], v[46:47]
	v_cndmask_b32_e64 v45, v222, v46, s[6:7]
	v_cndmask_b32_e64 v44, v222, v47, s[8:9]
	v_pk_fma_f32 v[238:239], v[66:67], v[216:217], v[238:239]
	v_cndmask_b32_e64 v47, v222, v238, s[10:11]
	v_cndmask_b32_e64 v46, v222, v239, s[12:13]
	v_pk_fma_f32 v[240:241], v[68:69], v[216:217], v[240:241]
	v_cndmask_b32_e64 v50, v222, v240, s[14:15]
	v_cndmask_b32_e64 v48, v222, v241, s[16:17]
	v_pk_fma_f32 v[242:243], v[70:71], v[216:217], v[242:243]
	v_cndmask_b32_e64 v59, v222, v242, s[18:19]
	v_cndmask_b32_e64 v57, v222, v243, s[20:21]
	ds_read_b128 v[68:71], v25 offset:32768
	ds_read_b128 v[100:103], v25 offset:33280
	ds_read_b128 v[152:155], v26 offset:32768
	ds_read_b128 v[178:181], v26 offset:33280
	v_mfma_f32_16x16x32_bf16 v[52:55], v[52:55], v[4:7], 0
	v_mfma_f32_16x16x32_bf16 v[64:67], v[170:173], v[0:3], v[52:55]
	v_mfma_f32_16x16x32_bf16 v[60:63], v[60:63], v[4:7], 0
	s_nop 4
	ds_read2_b32 v[54:55], v235 offset0:192 offset1:193
	ds_read2_b32 v[238:239], v235 offset0:194 offset1:195
	ds_read2_b32 v[240:241], v235 offset0:196 offset1:197
	ds_read2_b32 v[242:243], v235 offset0:198 offset1:199
	s_waitcnt lgkmcnt(0)
	v_pk_fma_f32 v[54:55], v[64:65], v[216:217], v[54:55]
	v_cndmask_b32_e64 v53, v222, v54, s[6:7]
	v_cndmask_b32_e64 v52, v222, v55, s[8:9]
	v_mfma_f32_16x16x32_bf16 v[60:63], v[174:177], v[0:3], v[60:63]
	v_pk_fma_f32 v[238:239], v[66:67], v[216:217], v[238:239]
	v_cndmask_b32_e64 v55, v222, v238, s[10:11]
	v_cndmask_b32_e64 v54, v222, v239, s[12:13]
	s_nop 3
	s_nop 0
	v_pk_fma_f32 v[240:241], v[60:61], v[216:217], v[240:241]
	v_cndmask_b32_e64 v58, v222, v240, s[14:15]
	v_cndmask_b32_e64 v56, v222, v241, s[16:17]
	v_pk_fma_f32 v[242:243], v[62:63], v[216:217], v[242:243]
	v_cndmask_b32_e64 v67, v222, v242, s[18:19]
	v_cndmask_b32_e64 v65, v222, v243, s[20:21]
	ds_read_b128 v[170:173], v25 offset:40960
	ds_read_b128 v[174:177], v25 offset:41472
	ds_read_b128 v[182:185], v26 offset:40960
	ds_read_b128 v[186:189], v26 offset:41472
	v_mfma_f32_16x16x32_bf16 v[60:63], v[68:71], v[4:7], 0
	v_mfma_f32_16x16x32_bf16 v[68:71], v[100:103], v[4:7], 0
	v_mfma_f32_16x16x32_bf16 v[100:103], v[152:155], v[0:3], v[60:63]
	s_nop 4
	ds_read2_b32 v[62:63], v236 offset0:0 offset1:1
	v_mfma_f32_16x16x32_bf16 v[68:71], v[178:181], v[0:3], v[68:71]
	ds_read2_b32 v[238:239], v236 offset0:2 offset1:3
	ds_read2_b32 v[240:241], v236 offset0:4 offset1:5
	ds_read2_b32 v[242:243], v236 offset0:6 offset1:7
	s_waitcnt lgkmcnt(0)
	v_pk_fma_f32 v[62:63], v[100:101], v[216:217], v[62:63]
	v_cndmask_b32_e64 v61, v222, v62, s[6:7]
	v_cndmask_b32_e64 v60, v222, v63, s[8:9]
	v_pk_fma_f32 v[238:239], v[102:103], v[216:217], v[238:239]
	v_cndmask_b32_e64 v63, v222, v238, s[10:11]
	v_cndmask_b32_e64 v62, v222, v239, s[12:13]
	v_pk_fma_f32 v[240:241], v[68:69], v[216:217], v[240:241]
	v_cndmask_b32_e64 v66, v222, v240, s[14:15]
	v_cndmask_b32_e64 v64, v222, v241, s[16:17]
	v_pk_fma_f32 v[242:243], v[70:71], v[216:217], v[242:243]
	v_cndmask_b32_e64 v102, v222, v242, s[18:19]
	v_cndmask_b32_e64 v100, v222, v243, s[20:21]
	ds_read_b128 v[178:181], v25 offset:49152
	ds_read_b128 v[190:193], v25 offset:49664
	ds_read_b128 v[194:197], v26 offset:49152
	ds_read_b128 v[198:201], v26 offset:49664
	v_mfma_f32_16x16x32_bf16 v[68:71], v[170:173], v[4:7], 0
	v_mfma_f32_16x16x32_bf16 v[170:173], v[182:185], v[0:3], v[68:71]
	v_mfma_f32_16x16x32_bf16 v[152:155], v[174:177], v[4:7], 0
	s_nop 4
	ds_read2_b32 v[70:71], v236 offset0:64 offset1:65
	ds_read2_b32 v[238:239], v236 offset0:66 offset1:67
	ds_read2_b32 v[240:241], v236 offset0:68 offset1:69
	ds_read2_b32 v[242:243], v236 offset0:70 offset1:71
	s_waitcnt lgkmcnt(0)
	v_pk_fma_f32 v[70:71], v[170:171], v[216:217], v[70:71]
	v_cndmask_b32_e64 v69, v222, v70, s[6:7]
	v_cndmask_b32_e64 v68, v222, v71, s[8:9]
	v_mfma_f32_16x16x32_bf16 v[174:177], v[186:189], v[0:3], v[152:155]
	v_pk_fma_f32 v[238:239], v[172:173], v[216:217], v[238:239]
	v_cndmask_b32_e64 v71, v222, v238, s[10:11]
	v_cndmask_b32_e64 v70, v222, v239, s[12:13]
	s_nop 3
	s_nop 0
	v_pk_fma_f32 v[240:241], v[174:175], v[216:217], v[240:241]
	v_cndmask_b32_e64 v101, v222, v240, s[14:15]
	v_cndmask_b32_e64 v99, v222, v241, s[16:17]
	v_pk_fma_f32 v[242:243], v[176:177], v[216:217], v[242:243]
	v_cndmask_b32_e64 v155, v222, v242, s[18:19]
	v_cndmask_b32_e64 v153, v222, v243, s[20:21]
	ds_read_b128 v[182:185], v25 offset:57344
	ds_read_b128 v[186:189], v25 offset:57856
	ds_read_b128 v[202:205], v26 offset:57344
	ds_read_b128 v[206:209], v26 offset:57856
	v_mfma_f32_16x16x32_bf16 v[170:173], v[178:181], v[4:7], 0
	ds_read2_b32 v[26:27], v236 offset0:128 offset1:129
	v_mfma_f32_16x16x32_bf16 v[170:173], v[194:197], v[0:3], v[170:173]
	v_mfma_f32_16x16x32_bf16 v[174:177], v[190:193], v[4:7], 0
	v_mfma_f32_16x16x32_bf16 v[174:177], v[198:201], v[0:3], v[174:177]
	ds_read2_b32 v[238:239], v236 offset0:130 offset1:131
	ds_read2_b32 v[240:241], v236 offset0:132 offset1:133
	ds_read2_b32 v[242:243], v236 offset0:134 offset1:135
	s_waitcnt lgkmcnt(0)
	s_nop 4
	v_pk_fma_f32 v[26:27], v[170:171], v[216:217], v[26:27]
	v_cndmask_b32_e64 v104, v222, v26, s[6:7]
	v_cndmask_b32_e64 v103, v222, v27, s[8:9]
	v_pk_fma_f32 v[238:239], v[172:173], v[216:217], v[238:239]
	v_cndmask_b32_e64 v151, v222, v238, s[10:11]
	v_cndmask_b32_e64 v105, v222, v239, s[12:13]
	v_pk_fma_f32 v[240:241], v[174:175], v[216:217], v[240:241]
	v_cndmask_b32_e64 v154, v222, v240, s[14:15]
	v_cndmask_b32_e64 v152, v222, v241, s[16:17]
	v_pk_fma_f32 v[242:243], v[176:177], v[216:217], v[242:243]
	v_cndmask_b32_e64 v175, v222, v242, s[18:19]
	v_cndmask_b32_e64 v173, v222, v243, s[20:21]
	v_mfma_f32_16x16x32_bf16 v[176:179], v[182:185], v[4:7], 0
	v_mfma_f32_16x16x32_bf16 v[4:7], v[186:189], v[4:7], 0
	v_mfma_f32_16x16x32_bf16 v[176:179], v[202:205], v[0:3], v[176:179]
	v_mfma_f32_16x16x32_bf16 v[0:3], v[206:209], v[0:3], v[4:7]
	s_nop 5
	ds_read2_b32 v[4:5], v236 offset0:192 offset1:193
	ds_read2_b32 v[238:239], v236 offset0:194 offset1:195
	ds_read2_b32 v[240:241], v236 offset0:196 offset1:197
	ds_read2_b32 v[242:243], v236 offset0:198 offset1:199
	s_waitcnt lgkmcnt(0)
	v_pk_fma_f32 v[4:5], v[176:177], v[216:217], v[4:5]
	v_cndmask_b32_e64 v170, v222, v4, s[6:7]
	v_cndmask_b32_e64 v167, v222, v5, s[8:9]
	v_pk_fma_f32 v[238:239], v[178:179], v[216:217], v[238:239]
	v_cndmask_b32_e64 v172, v222, v238, s[10:11]
	v_cndmask_b32_e64 v171, v222, v239, s[12:13]
	v_pk_fma_f32 v[240:241], v[0:1], v[216:217], v[240:241]
	v_cndmask_b32_e64 v176, v222, v240, s[14:15]
	v_cndmask_b32_e64 v174, v222, v241, s[16:17]
	v_pk_fma_f32 v[242:243], v[2:3], v[216:217], v[242:243]
	v_cndmask_b32_e64 v178, v222, v242, s[18:19]
	v_cndmask_b32_e64 v177, v222, v243, s[20:21]
	v_max3_f32 v0, v97, v30, v29
	v_max3_f32 v0, v0, v32, v31
	v_max3_f32 v0, v0, v34, v33
	v_max3_f32 v0, v0, v43, v41
	v_max3_f32 v0, v0, v37, v35
	v_max3_f32 v0, v0, v39, v38
	v_max3_f32 v0, v0, v42, v40
	v_max3_f32 v0, v0, v51, v49
	v_max3_f32 v0, v0, v45, v44
	v_max3_f32 v0, v0, v47, v46
	v_max3_f32 v0, v0, v50, v48
	v_max3_f32 v0, v0, v59, v57
	v_max3_f32 v0, v0, v53, v52
	v_max3_f32 v0, v0, v55, v54
	v_max3_f32 v0, v0, v58, v56
	v_max3_f32 v0, v0, v67, v65
	v_max3_f32 v0, v0, v61, v60
	v_max3_f32 v0, v0, v63, v62
	v_max3_f32 v0, v0, v66, v64
	v_max3_f32 v0, v0, v102, v100
	v_max3_f32 v0, v0, v69, v68
	v_max3_f32 v0, v0, v71, v70
	v_max3_f32 v0, v0, v101, v99
	v_max3_f32 v0, v0, v155, v153
	v_max3_f32 v0, v0, v104, v103
	v_max3_f32 v0, v0, v151, v105
	v_max3_f32 v0, v0, v154, v152
	v_max3_f32 v0, v0, v175, v173
	v_max3_f32 v0, v0, v170, v167
	v_max3_f32 v0, v0, v172, v171
	v_max3_f32 v0, v0, v176, v174
	v_max3_f32 v0, v0, v178, v177
	ds_bpermute_b32 v1, v114, v0
	s_waitcnt lgkmcnt(0)
	v_max_f32_e32 v1, v1, v1
	v_max_f32_e32 v0, v0, v1
	ds_bpermute_b32 v1, v115, v0
	s_waitcnt lgkmcnt(0)
	v_max_f32_e32 v1, v1, v1
	v_max_f32_e32 v179, v0, v1
	v_sub_f32_e32 v0, v97, v179
	v_exp_f32_e32 v204, v0
	s_nop 0
	v_pk_mul_f32 v[24:25], v[8:9], v[204:205] op_sel_hi:[1,0]
	v_pk_mul_f32 v[8:9], v[12:13], v[204:205] op_sel_hi:[1,0]
	v_lshl_add_u32 v12, v36, 3, v112
	v_xor_b32_e32 v13, v12, v107
	v_lshl_add_u32 v13, v13, 4, v113
	v_pk_mul_f32 v[26:27], v[10:11], v[204:205] op_sel_hi:[1,0]
	v_pk_mul_f32 v[10:11], v[14:15], v[204:205] op_sel_hi:[1,0]
	v_pk_mul_f32 v[6:7], v[18:19], v[204:205] op_sel_hi:[1,0]
	v_pk_mul_f32 v[4:5], v[16:17], v[204:205] op_sel_hi:[1,0]
	v_pk_mul_f32 v[0:1], v[20:21], v[204:205] op_sel_hi:[1,0]
	ds_read_b128 v[14:17], v13
	ds_read_b128 v[18:21], v13 offset:20480
	ds_read_b128 v[180:183], v13 offset:40960
	ds_read_b128 v[184:187], v13 offset:61440
	v_add_u32_e32 v13, 8, v12
	v_xor_b32_e32 v13, v13, v107
	v_lshl_add_u32 v13, v13, 4, v113
	ds_read_b128 v[188:191], v13
	ds_read_b128 v[192:195], v13 offset:20480
	ds_read_b128 v[196:199], v13 offset:40960
	ds_read_b128 v[200:203], v13 offset:61440
	v_pk_mul_f32 v[2:3], v[22:23], v[204:205] op_sel_hi:[1,0]
	v_mul_f32_e32 v218, v28, v204
	v_mov_b32_e32 v219, 0
	v_sub_f32_e32 v224, v30, v179
	v_sub_f32_e32 v225, v29, v179
	v_exp_f32_e32 v224, v224
	v_sub_f32_e32 v226, v32, v179
	v_exp_f32_e32 v225, v225
	v_sub_f32_e32 v227, v31, v179
	v_exp_f32_e32 v226, v226
	v_sub_f32_e32 v228, v34, v179
	v_exp_f32_e32 v227, v227
	v_sub_f32_e32 v229, v33, v179
	v_exp_f32_e32 v228, v228
	v_pk_add_f32 v[218:219], v[218:219], v[224:225]
	v_sub_f32_e32 v230, v43, v179
	v_exp_f32_e32 v229, v229
	v_pk_add_f32 v[218:219], v[218:219], v[226:227]
	v_sub_f32_e32 v231, v41, v179
	v_exp_f32_e32 v230, v230
	v_cvt_pk_bf16_f32 v28, v224, v225
	v_exp_f32_e32 v231, v231
	v_cvt_pk_bf16_f32 v29, v226, v227
	v_pk_add_f32 v[218:219], v[218:219], v[228:229]
	v_cvt_pk_bf16_f32 v30, v228, v229
	v_cvt_pk_bf16_f32 v31, v230, v231
	v_pk_add_f32 v[218:219], v[218:219], v[230:231]
	s_waitcnt lgkmcnt(7)
	v_mfma_f32_16x16x32_bf16 v[14:17], v[14:17], v[28:31], v[24:27]
	s_waitcnt lgkmcnt(6)
	v_mfma_f32_16x16x32_bf16 v[8:11], v[18:21], v[28:31], v[8:11]
	s_waitcnt lgkmcnt(5)
	v_mfma_f32_16x16x32_bf16 v[4:7], v[180:183], v[28:31], v[4:7]
	s_waitcnt lgkmcnt(4)
	v_mfma_f32_16x16x32_bf16 v[0:3], v[184:187], v[28:31], v[0:3]
	v_add_u32_e32 v13, 16, v12
	v_xor_b32_e32 v13, v13, v107
	v_lshl_add_u32 v13, v13, 4, v113
	ds_read_b128 v[18:21], v13
	ds_read_b128 v[22:25], v13 offset:20480
	ds_read_b128 v[26:29], v13 offset:40960
	ds_read_b128 v[30:33], v13 offset:61440
	v_sub_f32_e32 v224, v37, v179
	v_sub_f32_e32 v225, v35, v179
	v_exp_f32_e32 v224, v224
	v_sub_f32_e32 v226, v39, v179
	v_exp_f32_e32 v225, v225
	v_sub_f32_e32 v227, v38, v179
	v_exp_f32_e32 v226, v226
	v_sub_f32_e32 v228, v42, v179
	v_exp_f32_e32 v227, v227
	v_sub_f32_e32 v229, v40, v179
	v_exp_f32_e32 v228, v228
	v_pk_add_f32 v[218:219], v[218:219], v[224:225]
	v_sub_f32_e32 v230, v51, v179
	v_exp_f32_e32 v229, v229
	v_pk_add_f32 v[218:219], v[218:219], v[226:227]
	v_sub_f32_e32 v231, v49, v179
	v_exp_f32_e32 v230, v230
	v_cvt_pk_bf16_f32 v34, v224, v225
	v_exp_f32_e32 v231, v231
	v_cvt_pk_bf16_f32 v35, v226, v227
	v_pk_add_f32 v[218:219], v[218:219], v[228:229]
	v_cvt_pk_bf16_f32 v36, v228, v229
	v_cvt_pk_bf16_f32 v37, v230, v231
	v_pk_add_f32 v[218:219], v[218:219], v[230:231]
	s_waitcnt lgkmcnt(7)
	s_nop 0
	v_mfma_f32_16x16x32_bf16 v[14:17], v[188:191], v[34:37], v[14:17]
	s_waitcnt lgkmcnt(6)
	v_mfma_f32_16x16x32_bf16 v[8:11], v[192:195], v[34:37], v[8:11]
	s_waitcnt lgkmcnt(5)
	v_mfma_f32_16x16x32_bf16 v[4:7], v[196:199], v[34:37], v[4:7]
	s_waitcnt lgkmcnt(4)
	v_mfma_f32_16x16x32_bf16 v[0:3], v[200:203], v[34:37], v[0:3]
	v_add_u32_e32 v13, 24, v12
	v_xor_b32_e32 v13, v13, v107
	v_lshl_add_u32 v13, v13, 4, v113
	ds_read_b128 v[34:37], v13
	ds_read_b128 v[38:41], v13 offset:20480
	ds_read_b128 v[180:183], v13 offset:40960
	ds_read_b128 v[184:187], v13 offset:61440
	v_sub_f32_e32 v224, v45, v179
	v_sub_f32_e32 v225, v44, v179
	v_exp_f32_e32 v224, v224
	v_sub_f32_e32 v226, v47, v179
	v_exp_f32_e32 v225, v225
	v_sub_f32_e32 v227, v46, v179
	v_exp_f32_e32 v226, v226
	v_sub_f32_e32 v228, v50, v179
	v_exp_f32_e32 v227, v227
	v_sub_f32_e32 v229, v48, v179
	v_exp_f32_e32 v228, v228
	v_pk_add_f32 v[218:219], v[218:219], v[224:225]
	v_sub_f32_e32 v230, v59, v179
	v_exp_f32_e32 v229, v229
	v_pk_add_f32 v[218:219], v[218:219], v[226:227]
	v_sub_f32_e32 v231, v57, v179
	v_exp_f32_e32 v230, v230
	v_cvt_pk_bf16_f32 v42, v224, v225
	v_exp_f32_e32 v231, v231
	v_cvt_pk_bf16_f32 v43, v226, v227
	v_pk_add_f32 v[218:219], v[218:219], v[228:229]
	v_cvt_pk_bf16_f32 v44, v228, v229
	v_cvt_pk_bf16_f32 v45, v230, v231
	v_pk_add_f32 v[218:219], v[218:219], v[230:231]
	s_waitcnt lgkmcnt(7)
	s_nop 0
	v_mfma_f32_16x16x32_bf16 v[14:17], v[18:21], v[42:45], v[14:17]
	s_waitcnt lgkmcnt(6)
	v_mfma_f32_16x16x32_bf16 v[8:11], v[22:25], v[42:45], v[8:11]
	s_waitcnt lgkmcnt(5)
	v_mfma_f32_16x16x32_bf16 v[4:7], v[26:29], v[42:45], v[4:7]
	s_waitcnt lgkmcnt(4)
	v_mfma_f32_16x16x32_bf16 v[0:3], v[30:33], v[42:45], v[0:3]
	v_add_u32_e32 v13, 32, v12
	v_xor_b32_e32 v13, v13, v107
	v_lshl_add_u32 v13, v13, 4, v113
	ds_read_b128 v[18:21], v13
	ds_read_b128 v[22:25], v13 offset:20480
	ds_read_b128 v[26:29], v13 offset:40960
	ds_read_b128 v[30:33], v13 offset:61440
	v_sub_f32_e32 v224, v53, v179
	v_sub_f32_e32 v225, v52, v179
	v_exp_f32_e32 v224, v224
	v_sub_f32_e32 v226, v55, v179
	v_exp_f32_e32 v225, v225
	v_sub_f32_e32 v227, v54, v179
	v_exp_f32_e32 v226, v226
	v_sub_f32_e32 v228, v58, v179
	v_exp_f32_e32 v227, v227
	v_sub_f32_e32 v229, v56, v179
	v_exp_f32_e32 v228, v228
	v_pk_add_f32 v[218:219], v[218:219], v[224:225]
	v_sub_f32_e32 v230, v67, v179
	v_exp_f32_e32 v229, v229
	v_pk_add_f32 v[218:219], v[218:219], v[226:227]
	v_sub_f32_e32 v231, v65, v179
	v_exp_f32_e32 v230, v230
	v_cvt_pk_bf16_f32 v42, v224, v225
	v_exp_f32_e32 v231, v231
	v_cvt_pk_bf16_f32 v43, v226, v227
	v_pk_add_f32 v[218:219], v[218:219], v[228:229]
	v_cvt_pk_bf16_f32 v44, v228, v229
	v_cvt_pk_bf16_f32 v45, v230, v231
	v_pk_add_f32 v[218:219], v[218:219], v[230:231]
	s_waitcnt lgkmcnt(7)
	s_nop 0
	v_mfma_f32_16x16x32_bf16 v[14:17], v[34:37], v[42:45], v[14:17]
	s_waitcnt lgkmcnt(6)
	v_mfma_f32_16x16x32_bf16 v[8:11], v[38:41], v[42:45], v[8:11]
	s_waitcnt lgkmcnt(5)
	v_mfma_f32_16x16x32_bf16 v[4:7], v[180:183], v[42:45], v[4:7]
	s_waitcnt lgkmcnt(4)
	v_mfma_f32_16x16x32_bf16 v[0:3], v[184:187], v[42:45], v[0:3]
	v_add_u32_e32 v13, 40, v12
	v_xor_b32_e32 v13, v13, v107
	v_lshl_add_u32 v13, v13, 4, v113
	ds_read_b128 v[34:37], v13
	ds_read_b128 v[38:41], v13 offset:20480
	ds_read_b128 v[42:45], v13 offset:40960
	ds_read_b128 v[46:49], v13 offset:61440
	v_sub_f32_e32 v224, v61, v179
	v_sub_f32_e32 v225, v60, v179
	v_exp_f32_e32 v224, v224
	v_sub_f32_e32 v226, v63, v179
	v_exp_f32_e32 v225, v225
	v_sub_f32_e32 v227, v62, v179
	v_exp_f32_e32 v226, v226
	v_sub_f32_e32 v228, v66, v179
	v_exp_f32_e32 v227, v227
	v_sub_f32_e32 v229, v64, v179
	v_exp_f32_e32 v228, v228
	v_pk_add_f32 v[218:219], v[218:219], v[224:225]
	v_sub_f32_e32 v230, v102, v179
	v_exp_f32_e32 v229, v229
	v_pk_add_f32 v[218:219], v[218:219], v[226:227]
	v_sub_f32_e32 v231, v100, v179
	v_exp_f32_e32 v230, v230
	v_cvt_pk_bf16_f32 v50, v224, v225
	v_exp_f32_e32 v231, v231
	v_cvt_pk_bf16_f32 v51, v226, v227
	v_pk_add_f32 v[218:219], v[218:219], v[228:229]
	v_cvt_pk_bf16_f32 v52, v228, v229
	v_cvt_pk_bf16_f32 v53, v230, v231
	v_pk_add_f32 v[218:219], v[218:219], v[230:231]
	s_waitcnt lgkmcnt(7)
	s_nop 0
	v_mfma_f32_16x16x32_bf16 v[14:17], v[18:21], v[50:53], v[14:17]
	s_waitcnt lgkmcnt(6)
	v_mfma_f32_16x16x32_bf16 v[8:11], v[22:25], v[50:53], v[8:11]
	s_waitcnt lgkmcnt(5)
	v_mfma_f32_16x16x32_bf16 v[4:7], v[26:29], v[50:53], v[4:7]
	s_waitcnt lgkmcnt(4)
	v_mfma_f32_16x16x32_bf16 v[0:3], v[30:33], v[50:53], v[0:3]
	v_add_u32_e32 v13, 48, v12
	v_xor_b32_e32 v13, v13, v107
	v_lshl_add_u32 v13, v13, 4, v113
	ds_read_b128 v[18:21], v13
	ds_read_b128 v[22:25], v13 offset:20480
	ds_read_b128 v[26:29], v13 offset:40960
	ds_read_b128 v[30:33], v13 offset:61440
	v_sub_f32_e32 v224, v69, v179
	v_sub_f32_e32 v225, v68, v179
	v_exp_f32_e32 v224, v224
	v_sub_f32_e32 v226, v71, v179
	v_exp_f32_e32 v225, v225
	v_sub_f32_e32 v227, v70, v179
	v_exp_f32_e32 v226, v226
	v_sub_f32_e32 v228, v101, v179
	v_exp_f32_e32 v227, v227
	v_sub_f32_e32 v229, v99, v179
	v_exp_f32_e32 v228, v228
	v_pk_add_f32 v[218:219], v[218:219], v[224:225]
	v_sub_f32_e32 v230, v155, v179
	v_exp_f32_e32 v229, v229
	v_pk_add_f32 v[218:219], v[218:219], v[226:227]
	v_sub_f32_e32 v231, v153, v179
	v_exp_f32_e32 v230, v230
	v_cvt_pk_bf16_f32 v50, v224, v225
	v_exp_f32_e32 v231, v231
	v_cvt_pk_bf16_f32 v51, v226, v227
	v_pk_add_f32 v[218:219], v[218:219], v[228:229]
	v_cvt_pk_bf16_f32 v52, v228, v229
	v_cvt_pk_bf16_f32 v53, v230, v231
	v_pk_add_f32 v[218:219], v[218:219], v[230:231]
	s_waitcnt lgkmcnt(7)
	s_nop 0
	v_mfma_f32_16x16x32_bf16 v[14:17], v[34:37], v[50:53], v[14:17]
	s_waitcnt lgkmcnt(6)
	v_mfma_f32_16x16x32_bf16 v[8:11], v[38:41], v[50:53], v[8:11]
	s_waitcnt lgkmcnt(5)
	v_mfma_f32_16x16x32_bf16 v[4:7], v[42:45], v[50:53], v[4:7]
	s_waitcnt lgkmcnt(4)
	v_mfma_f32_16x16x32_bf16 v[0:3], v[46:49], v[50:53], v[0:3]
	v_add_u32_e32 v12, 56, v12
	v_xor_b32_e32 v12, v12, v107
	v_lshl_add_u32 v12, v12, 4, v113
	ds_read_b128 v[34:37], v12
	ds_read_b128 v[38:41], v12 offset:20480
	ds_read_b128 v[42:45], v12 offset:40960
	ds_read_b128 v[46:49], v12 offset:61440
	v_sub_f32_e32 v224, v104, v179
	v_sub_f32_e32 v225, v103, v179
	v_exp_f32_e32 v224, v224
	v_sub_f32_e32 v226, v151, v179
	v_exp_f32_e32 v225, v225
	v_sub_f32_e32 v227, v105, v179
	v_exp_f32_e32 v226, v226
	v_sub_f32_e32 v228, v154, v179
	v_exp_f32_e32 v227, v227
	v_sub_f32_e32 v229, v152, v179
	v_exp_f32_e32 v228, v228
	v_pk_add_f32 v[218:219], v[218:219], v[224:225]
	v_sub_f32_e32 v230, v175, v179
	v_exp_f32_e32 v229, v229
	v_pk_add_f32 v[218:219], v[218:219], v[226:227]
	v_sub_f32_e32 v231, v173, v179
	v_exp_f32_e32 v230, v230
	v_cvt_pk_bf16_f32 v50, v224, v225
	v_exp_f32_e32 v231, v231
	v_cvt_pk_bf16_f32 v51, v226, v227
	v_pk_add_f32 v[218:219], v[218:219], v[228:229]
	v_cvt_pk_bf16_f32 v52, v228, v229
	v_cvt_pk_bf16_f32 v53, v230, v231
	v_pk_add_f32 v[218:219], v[218:219], v[230:231]
	s_waitcnt lgkmcnt(7)
	v_mfma_f32_16x16x32_bf16 v[12:15], v[18:21], v[50:53], v[14:17]
	s_waitcnt lgkmcnt(6)
	v_mfma_f32_16x16x32_bf16 v[8:11], v[22:25], v[50:53], v[8:11]
	s_waitcnt lgkmcnt(5)
	v_mfma_f32_16x16x32_bf16 v[4:7], v[26:29], v[50:53], v[4:7]
	s_waitcnt lgkmcnt(4)
	v_mfma_f32_16x16x32_bf16 v[0:3], v[30:33], v[50:53], v[0:3]
	v_sub_f32_e32 v224, v170, v179
	v_sub_f32_e32 v225, v167, v179
	v_exp_f32_e32 v224, v224
	v_sub_f32_e32 v226, v172, v179
	v_exp_f32_e32 v225, v225
	v_sub_f32_e32 v227, v171, v179
	v_exp_f32_e32 v226, v226
	v_sub_f32_e32 v228, v176, v179
	v_exp_f32_e32 v227, v227
	v_sub_f32_e32 v229, v174, v179
	v_exp_f32_e32 v228, v228
	v_pk_add_f32 v[218:219], v[218:219], v[224:225]
	v_sub_f32_e32 v230, v178, v179
	v_exp_f32_e32 v229, v229
	v_pk_add_f32 v[218:219], v[218:219], v[226:227]
	v_sub_f32_e32 v231, v177, v179
	v_exp_f32_e32 v230, v230
	v_cvt_pk_bf16_f32 v16, v224, v225
	v_exp_f32_e32 v231, v231
	v_cvt_pk_bf16_f32 v17, v226, v227
	v_pk_add_f32 v[218:219], v[218:219], v[228:229]
	v_cvt_pk_bf16_f32 v18, v228, v229
	v_cvt_pk_bf16_f32 v19, v230, v231
	v_pk_add_f32 v[218:219], v[218:219], v[230:231]
	v_add_f32_e32 v25, v218, v219
	s_waitcnt lgkmcnt(3)
	s_nop 0
	v_mfma_f32_16x16x32_bf16 v[12:15], v[34:37], v[16:19], v[12:15]
	s_waitcnt lgkmcnt(2)
	v_mfma_f32_16x16x32_bf16 v[8:11], v[38:41], v[16:19], v[8:11]
	s_waitcnt lgkmcnt(1)
	v_mfma_f32_16x16x32_bf16 v[4:7], v[42:45], v[16:19], v[4:7]
	s_waitcnt lgkmcnt(0)
	v_mfma_f32_16x16x32_bf16 v[0:3], v[46:49], v[16:19], v[0:3]
	ds_bpermute_b32 v17, v114, v25
	v_or_b32_e32 v16, s62, v108
	v_mov_b32_e32 v99, v157
	s_add_i32 s61, s61, s3
	s_cmpk_gt_i32 s61, 0x7ff
	s_waitcnt lgkmcnt(0)
	v_add_f32_e32 v18, v25, v17
	ds_bpermute_b32 v19, v115, v18
	v_ashrrev_i32_e32 v17, 31, v16
	v_lshlrev_b64 v[16:17], 11, v[16:17]
	v_lshl_add_u64 v[16:17], s[26:27], 0, v[16:17]
	v_lshl_add_u64 v[16:17], v[16:17], 0, s[30:31]
	s_waitcnt lgkmcnt(0)
	v_add_f32_e32 v18, v18, v19
	v_div_scale_f32 v19, s[62:63], v18, v18, 1.0
	v_rcp_f32_e32 v20, v19
	v_div_scale_f32 v21, vcc, 1.0, v18, 1.0
	v_lshl_add_u64 v[16:17], v[16:17], 0, v[98:99]
	v_fma_f32 v22, -v19, v20, 1.0
	v_fmac_f32_e32 v20, v22, v20
	v_mul_f32_e32 v22, v21, v20
	v_fma_f32 v23, -v19, v22, v21
	v_fmac_f32_e32 v22, v23, v20
	v_fma_f32 v19, -v19, v22, v21
	v_div_fmas_f32 v19, v19, v20, v22
	v_div_fixup_f32 v18, v19, v18, 1.0
	v_pk_mul_f32 v[12:13], v[12:13], v[18:19] op_sel_hi:[1,0]
	v_pk_mul_f32 v[14:15], v[14:15], v[18:19] op_sel_hi:[1,0]
	v_pk_mul_f32 v[8:9], v[8:9], v[18:19] op_sel_hi:[1,0]
	v_pk_mul_f32 v[10:11], v[10:11], v[18:19] op_sel_hi:[1,0]
	v_pk_mul_f32 v[4:5], v[4:5], v[18:19] op_sel_hi:[1,0]
	v_pk_mul_f32 v[6:7], v[6:7], v[18:19] op_sel_hi:[1,0]
	v_pk_mul_f32 v[0:1], v[0:1], v[18:19] op_sel_hi:[1,0]
	v_pk_mul_f32 v[2:3], v[2:3], v[18:19] op_sel_hi:[1,0]
	v_cvt_pk_bf16_f32 v12, v12, v13
	v_cvt_pk_bf16_f32 v13, v14, v15
	v_cvt_pk_bf16_f32 v8, v8, v9
	v_cvt_pk_bf16_f32 v9, v10, v11
	v_cvt_pk_bf16_f32 v4, v4, v5
	v_cvt_pk_bf16_f32 v5, v6, v7
	v_cvt_pk_bf16_f32 v0, v0, v1
	v_cvt_pk_bf16_f32 v1, v2, v3
	global_store_dwordx2 v[16:17], v[12:13], off offset:1024
	global_store_dwordx2 v[16:17], v[8:9], off offset:1056
	global_store_dwordx2 v[16:17], v[4:5], off offset:1088
	global_store_dwordx2 v[16:17], v[0:1], off offset:1120
	s_barrier
	s_cbranch_scc1 .LBB0_306

.Lqjoin_299:
	ds_read_b128 v[8:11], v132
	ds_read_b128 v[12:15], v132 offset:512
	ds_read_b128 v[16:19], v133
	ds_read_b128 v[20:23], v133 offset:512
	ds_read_b128 v[24:27], v132 offset:4096
	ds_read_b128 v[28:31], v132 offset:4608
	ds_read_b128 v[32:35], v133 offset:4096
	ds_read_b128 v[36:39], v133 offset:4608
	s_waitcnt vmcnt(1) lgkmcnt(7)
	v_mfma_f32_16x16x32_bf16 v[8:11], v[8:11], v[4:7], 0
	s_waitcnt vmcnt(0) lgkmcnt(5)
	v_mfma_f32_16x16x32_bf16 v[68:71], v[16:19], v[0:3], v[8:11]
	v_mfma_f32_16x16x32_bf16 v[8:11], v[12:15], v[4:7], 0
	s_waitcnt lgkmcnt(4)
	v_mfma_f32_16x16x32_bf16 v[64:67], v[20:23], v[0:3], v[8:11]
	s_nop 4
	ds_read_b128 v[8:11], v132 offset:8192
	ds_read_b128 v[12:15], v132 offset:8704
	ds_read_b128 v[16:19], v133 offset:8192
	ds_read_b128 v[20:23], v133 offset:8704
	s_waitcnt lgkmcnt(7)
	v_mfma_f32_16x16x32_bf16 v[24:27], v[24:27], v[4:7], 0
	s_waitcnt lgkmcnt(5)
	v_mfma_f32_16x16x32_bf16 v[60:63], v[32:35], v[0:3], v[24:27]
	v_mfma_f32_16x16x32_bf16 v[24:27], v[28:31], v[4:7], 0
	s_waitcnt lgkmcnt(4)
	v_mfma_f32_16x16x32_bf16 v[56:59], v[36:39], v[0:3], v[24:27]
	s_nop 4
	ds_read_b128 v[24:27], v132 offset:12288
	ds_read_b128 v[28:31], v132 offset:12800
	ds_read_b128 v[32:35], v133 offset:12288
	ds_read_b128 v[36:39], v133 offset:12800
	s_waitcnt lgkmcnt(7)
	v_mfma_f32_16x16x32_bf16 v[8:11], v[8:11], v[4:7], 0
	s_waitcnt lgkmcnt(5)
	v_mfma_f32_16x16x32_bf16 v[52:55], v[16:19], v[0:3], v[8:11]
	v_mfma_f32_16x16x32_bf16 v[8:11], v[12:15], v[4:7], 0
	s_waitcnt lgkmcnt(4)
	v_mfma_f32_16x16x32_bf16 v[48:51], v[20:23], v[0:3], v[8:11]
	s_nop 4
	ds_read_b128 v[8:11], v132 offset:16384
	ds_read_b128 v[12:15], v132 offset:16896
	ds_read_b128 v[16:19], v133 offset:16384
	ds_read_b128 v[20:23], v133 offset:16896
	s_waitcnt lgkmcnt(7)
	v_mfma_f32_16x16x32_bf16 v[24:27], v[24:27], v[4:7], 0
	s_waitcnt lgkmcnt(5)
	v_mfma_f32_16x16x32_bf16 v[44:47], v[32:35], v[0:3], v[24:27]
	v_mfma_f32_16x16x32_bf16 v[24:27], v[28:31], v[4:7], 0
	s_waitcnt lgkmcnt(4)
	v_mfma_f32_16x16x32_bf16 v[40:43], v[36:39], v[0:3], v[24:27]
	s_nop 4
	ds_read_b128 v[24:27], v132 offset:20480
	ds_read_b128 v[152:155], v132 offset:20992
	ds_read_b128 v[28:31], v133 offset:20480
	ds_read_b128 v[170:173], v133 offset:20992
	s_waitcnt lgkmcnt(7)
	v_mfma_f32_16x16x32_bf16 v[8:11], v[8:11], v[4:7], 0
	s_waitcnt lgkmcnt(5)
	v_mfma_f32_16x16x32_bf16 v[36:39], v[16:19], v[0:3], v[8:11]
	v_mfma_f32_16x16x32_bf16 v[8:11], v[12:15], v[4:7], 0
	s_waitcnt lgkmcnt(4)
	v_mfma_f32_16x16x32_bf16 v[32:35], v[20:23], v[0:3], v[8:11]
	s_nop 4
	ds_read_b128 v[8:11], v132 offset:24576
	ds_read_b128 v[12:15], v132 offset:25088
	ds_read_b128 v[16:19], v133 offset:24576
	ds_read_b128 v[174:177], v133 offset:25088
	s_waitcnt lgkmcnt(7)
	v_mfma_f32_16x16x32_bf16 v[20:23], v[24:27], v[4:7], 0
	s_waitcnt lgkmcnt(5)
	v_mfma_f32_16x16x32_bf16 v[28:31], v[28:31], v[0:3], v[20:23]
	v_mfma_f32_16x16x32_bf16 v[20:23], v[152:155], v[4:7], 0
	s_waitcnt lgkmcnt(4)
	v_mfma_f32_16x16x32_bf16 v[24:27], v[170:173], v[0:3], v[20:23]
	s_nop 4
	ds_read_b128 v[152:155], v132 offset:28672
	ds_read_b128 v[170:173], v132 offset:29184
	ds_read_b128 v[178:181], v133 offset:28672
	ds_read_b128 v[182:185], v133 offset:29184
	s_waitcnt lgkmcnt(7)
	v_mfma_f32_16x16x32_bf16 v[8:11], v[8:11], v[4:7], 0
	s_waitcnt lgkmcnt(5)
	v_mfma_f32_16x16x32_bf16 v[20:23], v[16:19], v[0:3], v[8:11]
	v_mfma_f32_16x16x32_bf16 v[8:11], v[12:15], v[4:7], 0
	s_waitcnt lgkmcnt(4)
	v_mfma_f32_16x16x32_bf16 v[16:19], v[174:177], v[0:3], v[8:11]
	s_nop 4
	s_waitcnt lgkmcnt(3)
	v_mfma_f32_16x16x32_bf16 v[8:11], v[152:155], v[4:7], 0
	s_waitcnt lgkmcnt(1)
	v_mfma_f32_16x16x32_bf16 v[12:15], v[178:181], v[0:3], v[8:11]
	v_mfma_f32_16x16x32_bf16 v[8:11], v[170:173], v[4:7], 0
	s_waitcnt lgkmcnt(0)
	v_mfma_f32_16x16x32_bf16 v[8:11], v[182:185], v[0:3], v[8:11]
	s_nop 4
	s_mov_b32 s30, 0xff800000
	v_max3_f32 v97, v68, s30, v69
	v_max3_f32 v97, v97, v70, v71
	v_max3_f32 v97, v97, v64, v65
	v_max3_f32 v97, v97, v66, v67
	v_max3_f32 v97, v97, v60, v61
	v_max3_f32 v97, v97, v62, v63
	v_max3_f32 v97, v97, v56, v57
	v_max3_f32 v97, v97, v58, v59
	v_max3_f32 v97, v97, v52, v53
	v_max3_f32 v97, v97, v54, v55
	v_max3_f32 v97, v97, v48, v49
	v_max3_f32 v97, v97, v50, v51
	v_max3_f32 v97, v97, v44, v45
	v_max3_f32 v97, v97, v46, v47
	v_max3_f32 v97, v97, v40, v41
	v_max3_f32 v97, v97, v42, v43
	v_max3_f32 v97, v97, v36, v37
	v_max3_f32 v97, v97, v38, v39
	v_max3_f32 v97, v97, v32, v33
	v_max3_f32 v97, v97, v34, v35
	v_max3_f32 v97, v97, v28, v29
	v_max3_f32 v97, v97, v30, v31
	v_max3_f32 v97, v97, v24, v25
	v_max3_f32 v97, v97, v26, v27
	v_max3_f32 v97, v97, v20, v21
	v_max3_f32 v97, v97, v22, v23
	v_max3_f32 v97, v97, v16, v17
	v_max3_f32 v97, v97, v18, v19
	v_max3_f32 v97, v97, v12, v13
	v_max3_f32 v97, v97, v14, v15
	v_max3_f32 v97, v97, v8, v9
	v_max3_f32 v97, v97, v10, v11
	v_mul_f32_e32 v97, 0x3e38aa3b, v97
	ds_bpermute_b32 v99, v114, v97
	ds_read_b128 v[152:155], v134 offset:32768
	ds_read_b128 v[170:173], v134 offset:40960
	ds_read_b128 v[174:177], v134 offset:49152
	ds_read_b128 v[178:181], v134 offset:57344
	ds_read_b128 v[182:185], v135 offset:32768
	ds_read_b128 v[186:189], v135 offset:40960
	ds_read_b128 v[190:193], v135 offset:49152
	ds_read_b128 v[194:197], v135 offset:57344
	s_waitcnt lgkmcnt(8)
	v_max_f32_e32 v99, v99, v99
	v_max_f32_e32 v97, v97, v99
	ds_bpermute_b32 v99, v115, v97
	s_waitcnt lgkmcnt(0)
	v_max_f32_e32 v99, v99, v99
	v_max_f32_e32 v97, v97, v99
	v_sub_f32_e32 v99, 0xff800000, v97
	v_exp_f32_e32 v99, v99
	s_nop 0
	v_mul_f32_e32 v198, 0, v99
	v_mov_b32_e32 v199, v198
	v_mov_b32_e32 v200, v198
	v_mov_b32_e32 v201, v198
	v_mov_b32_e32 v206, v97
	v_mov_b32_e32 v207, v97
	v_mov_b32_e32 v208, s67
	v_mov_b32_e32 v209, s67
	v_mov_b32_e32 v210, 0
	v_mov_b32_e32 v211, 0
	v_pk_fma_f32 v[68:69], v[68:69], v[208:209], v[206:207] neg_lo:[0,0,1] neg_hi:[0,0,1]
	v_pk_fma_f32 v[70:71], v[70:71], v[208:209], v[206:207] neg_lo:[0,0,1] neg_hi:[0,0,1]
	v_exp_f32_e32 v68, v68
	v_pk_fma_f32 v[64:65], v[64:65], v[208:209], v[206:207] neg_lo:[0,0,1] neg_hi:[0,0,1]
	v_exp_f32_e32 v69, v69
	v_pk_fma_f32 v[66:67], v[66:67], v[208:209], v[206:207] neg_lo:[0,0,1] neg_hi:[0,0,1]
	v_exp_f32_e32 v70, v70
	v_exp_f32_e32 v71, v71
	v_exp_f32_e32 v212, v64
	v_pk_add_f32 v[210:211], v[210:211], v[68:69]
	v_exp_f32_e32 v213, v65
	v_pk_add_f32 v[210:211], v[210:211], v[70:71]
	v_exp_f32_e32 v214, v66
	v_exp_f32_e32 v215, v67
	v_pk_add_f32 v[210:211], v[210:211], v[212:213]
	v_cvt_pk_bf16_f32 v64, v68, v69
	v_pk_add_f32 v[210:211], v[210:211], v[214:215]
	v_cvt_pk_bf16_f32 v65, v70, v71
	v_cvt_pk_bf16_f32 v66, v212, v213
	v_cvt_pk_bf16_f32 v67, v214, v215
	s_nop 1
	v_mfma_f32_16x16x32_bf16 v[68:71], v[152:155], v[64:67], v[198:201]
	v_mfma_f32_16x16x32_bf16 v[152:155], v[170:173], v[64:67], v[198:201]
	v_mfma_f32_16x16x32_bf16 v[170:173], v[174:177], v[64:67], v[198:201]
	v_mfma_f32_16x16x32_bf16 v[64:67], v[178:181], v[64:67], v[198:201]
	ds_read_b128 v[174:177], v136 offset:32768
	ds_read_b128 v[178:181], v136 offset:40960
	s_nop 0
	ds_read_b128 v[198:201], v136 offset:49152
	ds_read_b128 v[202:205], v136 offset:57344
	v_pk_fma_f32 v[60:61], v[60:61], v[208:209], v[206:207] neg_lo:[0,0,1] neg_hi:[0,0,1]
	v_pk_fma_f32 v[62:63], v[62:63], v[208:209], v[206:207] neg_lo:[0,0,1] neg_hi:[0,0,1]
	v_exp_f32_e32 v60, v60
	v_pk_fma_f32 v[56:57], v[56:57], v[208:209], v[206:207] neg_lo:[0,0,1] neg_hi:[0,0,1]
	v_exp_f32_e32 v61, v61
	v_pk_fma_f32 v[58:59], v[58:59], v[208:209], v[206:207] neg_lo:[0,0,1] neg_hi:[0,0,1]
	v_exp_f32_e32 v62, v62
	v_exp_f32_e32 v63, v63
	v_exp_f32_e32 v212, v56
	v_pk_add_f32 v[210:211], v[210:211], v[60:61]
	v_exp_f32_e32 v213, v57
	v_pk_add_f32 v[210:211], v[210:211], v[62:63]
	v_exp_f32_e32 v214, v58
	v_exp_f32_e32 v215, v59
	v_pk_add_f32 v[210:211], v[210:211], v[212:213]
	v_cvt_pk_bf16_f32 v56, v60, v61
	v_pk_add_f32 v[210:211], v[210:211], v[214:215]
	v_cvt_pk_bf16_f32 v57, v62, v63
	v_cvt_pk_bf16_f32 v58, v212, v213
	v_cvt_pk_bf16_f32 v59, v214, v215
	s_nop 1
	v_mfma_f32_16x16x32_bf16 v[60:63], v[182:185], v[56:59], v[68:71]
	v_mfma_f32_16x16x32_bf16 v[68:71], v[186:189], v[56:59], v[152:155]
	v_mfma_f32_16x16x32_bf16 v[152:155], v[190:193], v[56:59], v[170:173]
	v_mfma_f32_16x16x32_bf16 v[56:59], v[194:197], v[56:59], v[64:67]
	s_nop 2
	ds_read_b128 v[64:67], v137 offset:32768
	ds_read_b128 v[170:173], v137 offset:40960
	ds_read_b128 v[182:185], v137 offset:49152
	ds_read_b128 v[186:189], v137 offset:57344
	v_pk_fma_f32 v[52:53], v[52:53], v[208:209], v[206:207] neg_lo:[0,0,1] neg_hi:[0,0,1]
	v_pk_fma_f32 v[54:55], v[54:55], v[208:209], v[206:207] neg_lo:[0,0,1] neg_hi:[0,0,1]
	v_exp_f32_e32 v52, v52
	v_pk_fma_f32 v[48:49], v[48:49], v[208:209], v[206:207] neg_lo:[0,0,1] neg_hi:[0,0,1]
	v_exp_f32_e32 v53, v53
	v_pk_fma_f32 v[50:51], v[50:51], v[208:209], v[206:207] neg_lo:[0,0,1] neg_hi:[0,0,1]
	v_exp_f32_e32 v54, v54
	v_exp_f32_e32 v55, v55
	v_exp_f32_e32 v212, v48
	v_pk_add_f32 v[210:211], v[210:211], v[52:53]
	v_exp_f32_e32 v213, v49
	v_pk_add_f32 v[210:211], v[210:211], v[54:55]
	v_exp_f32_e32 v214, v50
	v_exp_f32_e32 v215, v51
	v_pk_add_f32 v[210:211], v[210:211], v[212:213]
	v_cvt_pk_bf16_f32 v48, v52, v53
	v_pk_add_f32 v[210:211], v[210:211], v[214:215]
	v_cvt_pk_bf16_f32 v49, v54, v55
	v_cvt_pk_bf16_f32 v50, v212, v213
	v_cvt_pk_bf16_f32 v51, v214, v215
	s_waitcnt lgkmcnt(7)
	s_nop 0
	v_mfma_f32_16x16x32_bf16 v[52:55], v[174:177], v[48:51], v[60:63]
	s_waitcnt lgkmcnt(6)
	v_mfma_f32_16x16x32_bf16 v[60:63], v[178:181], v[48:51], v[68:71]
	s_waitcnt lgkmcnt(5)
	v_mfma_f32_16x16x32_bf16 v[68:71], v[198:201], v[48:51], v[152:155]
	s_waitcnt lgkmcnt(4)
	v_mfma_f32_16x16x32_bf16 v[48:51], v[202:205], v[48:51], v[56:59]
	s_nop 2
	ds_read_b128 v[56:59], v138 offset:32768
	ds_read_b128 v[152:155], v138 offset:40960
	ds_read_b128 v[174:177], v138 offset:49152
	ds_read_b128 v[178:181], v138 offset:57344
	v_pk_fma_f32 v[44:45], v[44:45], v[208:209], v[206:207] neg_lo:[0,0,1] neg_hi:[0,0,1]
	v_pk_fma_f32 v[46:47], v[46:47], v[208:209], v[206:207] neg_lo:[0,0,1] neg_hi:[0,0,1]
	v_exp_f32_e32 v44, v44
	v_pk_fma_f32 v[40:41], v[40:41], v[208:209], v[206:207] neg_lo:[0,0,1] neg_hi:[0,0,1]
	v_exp_f32_e32 v45, v45
	v_pk_fma_f32 v[42:43], v[42:43], v[208:209], v[206:207] neg_lo:[0,0,1] neg_hi:[0,0,1]
	v_exp_f32_e32 v46, v46
	v_exp_f32_e32 v47, v47
	v_exp_f32_e32 v212, v40
	v_pk_add_f32 v[210:211], v[210:211], v[44:45]
	v_exp_f32_e32 v213, v41
	v_pk_add_f32 v[210:211], v[210:211], v[46:47]
	v_exp_f32_e32 v214, v42
	v_exp_f32_e32 v215, v43
	v_pk_add_f32 v[210:211], v[210:211], v[212:213]
	v_cvt_pk_bf16_f32 v40, v44, v45
	v_pk_add_f32 v[210:211], v[210:211], v[214:215]
	v_cvt_pk_bf16_f32 v41, v46, v47
	v_cvt_pk_bf16_f32 v42, v212, v213
	v_cvt_pk_bf16_f32 v43, v214, v215
	s_waitcnt lgkmcnt(7)
	s_nop 0
	v_mfma_f32_16x16x32_bf16 v[44:47], v[64:67], v[40:43], v[52:55]
	s_waitcnt lgkmcnt(6)
	v_mfma_f32_16x16x32_bf16 v[52:55], v[170:173], v[40:43], v[60:63]
	s_waitcnt lgkmcnt(5)
	v_mfma_f32_16x16x32_bf16 v[60:63], v[182:185], v[40:43], v[68:71]
	s_waitcnt lgkmcnt(4)
; __device__ __forceinline__ unsigned cvt_pk_bf16(float lo, float hi) { const f32x2 v = (f32x2){lo, hi}; return __builtin_bit_cast(unsigned, __builtin_convertvector(v, bf16v2)); }
; #define AH_LDV(c, bufi) do { const int vaddr = vrow + (((vchunk0 + (c) * vcs + g) ^ qi) << 4); _Pragma("unroll") for (int dt = 0; dt < 4; ++dt) vf[bufi][dt] = *(const LAS bf16x8*)(lds + vaddr + dt * vpitch_dt); } while (0)
; template <bool LOC> ...
;     ...
;             else s[c][e] = a * SC; }
;     ...
;     for (int c = 0; c < 8; ++c) {
;         if (c < 7) AH_LDV(c + 1, (c + 1) & 1);
;         __builtin_amdgcn_sched_barrier(0);
;         float pe[8];
; #pragma unroll
;         for (int e = 0; e < 8; ++e) { pe[e] = __builtin_amdgcn_exp2f(s[c][e] - mx); lsum += pe[e]; }
;         u32x4 pw; pw.x = cvt_pk_bf16(pe[0], pe[1]); pw.y = cvt_pk_bf16(pe[2], pe[3]); pw.z = cvt_pk_bf16(pe[4], pe[5]); pw.w = cvt_pk_bf16(pe[6], pe[7]);
;         const bf16x8 pb = __builtin_bit_cast(bf16x8, pw);
; #pragma unroll
;         for (int dt = 0; dt < 4; ++dt) o[dt] = __builtin_amdgcn_mfma_f32_16x16x32_bf16(vf[c & 1][dt], pb, o[dt], 0, 0, 0);
;         __builtin_amdgcn_sched_barrier(0);
;     }
	v_mfma_f32_16x16x32_bf16 v[40:43], v[186:189], v[40:43], v[48:51]
	s_nop 2
	ds_read_b128 v[48:51], v139 offset:32768
	ds_read_b128 v[64:67], v139 offset:40960
	ds_read_b128 v[68:71], v139 offset:49152
	ds_read_b128 v[170:173], v139 offset:57344
	v_pk_fma_f32 v[36:37], v[36:37], v[208:209], v[206:207] neg_lo:[0,0,1] neg_hi:[0,0,1]
	v_pk_fma_f32 v[38:39], v[38:39], v[208:209], v[206:207] neg_lo:[0,0,1] neg_hi:[0,0,1]
	v_exp_f32_e32 v36, v36
	v_pk_fma_f32 v[32:33], v[32:33], v[208:209], v[206:207] neg_lo:[0,0,1] neg_hi:[0,0,1]
	v_exp_f32_e32 v37, v37
	v_pk_fma_f32 v[34:35], v[34:35], v[208:209], v[206:207] neg_lo:[0,0,1] neg_hi:[0,0,1]
	v_exp_f32_e32 v38, v38
	v_exp_f32_e32 v39, v39
	v_exp_f32_e32 v212, v32
	v_pk_add_f32 v[210:211], v[210:211], v[36:37]
	v_exp_f32_e32 v213, v33
	v_pk_add_f32 v[210:211], v[210:211], v[38:39]
	v_exp_f32_e32 v214, v34
	v_exp_f32_e32 v215, v35
	v_pk_add_f32 v[210:211], v[210:211], v[212:213]
	v_cvt_pk_bf16_f32 v32, v36, v37
	v_pk_add_f32 v[210:211], v[210:211], v[214:215]
	v_cvt_pk_bf16_f32 v33, v38, v39
	v_cvt_pk_bf16_f32 v34, v212, v213
	v_cvt_pk_bf16_f32 v35, v214, v215
	s_waitcnt lgkmcnt(7)
	s_nop 0
	v_mfma_f32_16x16x32_bf16 v[36:39], v[56:59], v[32:35], v[44:47]
	s_waitcnt lgkmcnt(6)
	v_mfma_f32_16x16x32_bf16 v[44:47], v[152:155], v[32:35], v[52:55]
	s_waitcnt lgkmcnt(5)
	v_mfma_f32_16x16x32_bf16 v[52:55], v[174:177], v[32:35], v[60:63]
	s_waitcnt lgkmcnt(4)
	v_mfma_f32_16x16x32_bf16 v[32:35], v[178:181], v[32:35], v[40:43]
	s_nop 2
	ds_read_b128 v[40:43], v140 offset:32768
	ds_read_b128 v[56:59], v140 offset:40960
	ds_read_b128 v[60:63], v140 offset:49152
	ds_read_b128 v[152:155], v140 offset:57344
	v_pk_fma_f32 v[28:29], v[28:29], v[208:209], v[206:207] neg_lo:[0,0,1] neg_hi:[0,0,1]
	v_pk_fma_f32 v[30:31], v[30:31], v[208:209], v[206:207] neg_lo:[0,0,1] neg_hi:[0,0,1]
	v_exp_f32_e32 v28, v28
	v_pk_fma_f32 v[24:25], v[24:25], v[208:209], v[206:207] neg_lo:[0,0,1] neg_hi:[0,0,1]
	v_exp_f32_e32 v29, v29
	v_pk_fma_f32 v[26:27], v[26:27], v[208:209], v[206:207] neg_lo:[0,0,1] neg_hi:[0,0,1]
	v_exp_f32_e32 v30, v30
	v_exp_f32_e32 v31, v31
	v_exp_f32_e32 v212, v24
	v_pk_add_f32 v[210:211], v[210:211], v[28:29]
	v_exp_f32_e32 v213, v25
	v_pk_add_f32 v[210:211], v[210:211], v[30:31]
	v_exp_f32_e32 v214, v26
	v_exp_f32_e32 v215, v27
	v_pk_add_f32 v[210:211], v[210:211], v[212:213]
	v_cvt_pk_bf16_f32 v24, v28, v29
	v_pk_add_f32 v[210:211], v[210:211], v[214:215]
	v_cvt_pk_bf16_f32 v25, v30, v31
	v_cvt_pk_bf16_f32 v26, v212, v213
	v_cvt_pk_bf16_f32 v27, v214, v215
	s_waitcnt lgkmcnt(7)
	s_nop 0
	v_mfma_f32_16x16x32_bf16 v[28:31], v[48:51], v[24:27], v[36:39]
	s_waitcnt lgkmcnt(6)
	v_mfma_f32_16x16x32_bf16 v[36:39], v[64:67], v[24:27], v[44:47]
	s_waitcnt lgkmcnt(5)
	v_mfma_f32_16x16x32_bf16 v[44:47], v[68:71], v[24:27], v[52:55]
	s_waitcnt lgkmcnt(4)
	v_mfma_f32_16x16x32_bf16 v[24:27], v[170:173], v[24:27], v[32:35]
	s_nop 2
	ds_read_b128 v[32:35], v141 offset:32768
	ds_read_b128 v[48:51], v141 offset:40960
	ds_read_b128 v[52:55], v141 offset:49152
	ds_read_b128 v[64:67], v141 offset:57344
	v_pk_fma_f32 v[20:21], v[20:21], v[208:209], v[206:207] neg_lo:[0,0,1] neg_hi:[0,0,1]
	v_pk_fma_f32 v[22:23], v[22:23], v[208:209], v[206:207] neg_lo:[0,0,1] neg_hi:[0,0,1]
	v_exp_f32_e32 v20, v20
	v_pk_fma_f32 v[16:17], v[16:17], v[208:209], v[206:207] neg_lo:[0,0,1] neg_hi:[0,0,1]
	v_exp_f32_e32 v21, v21
	v_pk_fma_f32 v[18:19], v[18:19], v[208:209], v[206:207] neg_lo:[0,0,1] neg_hi:[0,0,1]
	v_exp_f32_e32 v22, v22
	v_exp_f32_e32 v23, v23
	v_exp_f32_e32 v212, v16
	v_pk_add_f32 v[210:211], v[210:211], v[20:21]
	v_exp_f32_e32 v213, v17
	v_pk_add_f32 v[210:211], v[210:211], v[22:23]
	v_exp_f32_e32 v214, v18
	v_exp_f32_e32 v215, v19
	v_pk_add_f32 v[210:211], v[210:211], v[212:213]
	v_cvt_pk_bf16_f32 v16, v20, v21
	v_pk_add_f32 v[210:211], v[210:211], v[214:215]
	v_cvt_pk_bf16_f32 v17, v22, v23
	v_cvt_pk_bf16_f32 v18, v212, v213
	v_cvt_pk_bf16_f32 v19, v214, v215
	s_waitcnt lgkmcnt(7)
	s_nop 0
	v_mfma_f32_16x16x32_bf16 v[20:23], v[40:43], v[16:19], v[28:31]
	s_waitcnt lgkmcnt(6)
	v_mfma_f32_16x16x32_bf16 v[36:39], v[56:59], v[16:19], v[36:39]
	s_waitcnt lgkmcnt(5)
	v_mfma_f32_16x16x32_bf16 v[40:43], v[60:63], v[16:19], v[44:47]
	s_waitcnt lgkmcnt(4)
	v_mfma_f32_16x16x32_bf16 v[24:27], v[152:155], v[16:19], v[24:27]
	v_pk_fma_f32 v[12:13], v[12:13], v[208:209], v[206:207] neg_lo:[0,0,1] neg_hi:[0,0,1]
	v_pk_fma_f32 v[14:15], v[14:15], v[208:209], v[206:207] neg_lo:[0,0,1] neg_hi:[0,0,1]
	v_exp_f32_e32 v12, v12
	v_pk_fma_f32 v[8:9], v[8:9], v[208:209], v[206:207] neg_lo:[0,0,1] neg_hi:[0,0,1]
	v_exp_f32_e32 v13, v13
	v_pk_fma_f32 v[10:11], v[10:11], v[208:209], v[206:207] neg_lo:[0,0,1] neg_hi:[0,0,1]
	v_exp_f32_e32 v14, v14
	v_exp_f32_e32 v15, v15
	v_exp_f32_e32 v212, v8
	v_pk_add_f32 v[210:211], v[210:211], v[12:13]
	v_exp_f32_e32 v213, v9
	v_pk_add_f32 v[210:211], v[210:211], v[14:15]
	v_exp_f32_e32 v214, v10
	v_exp_f32_e32 v215, v11
	v_pk_add_f32 v[210:211], v[210:211], v[212:213]
	v_cvt_pk_bf16_f32 v44, v12, v13
	v_pk_add_f32 v[210:211], v[210:211], v[214:215]
	v_cvt_pk_bf16_f32 v45, v14, v15
	v_cvt_pk_bf16_f32 v46, v212, v213
	v_cvt_pk_bf16_f32 v47, v214, v215
	v_add_f32_e32 v28, v210, v211
	s_waitcnt lgkmcnt(3)
	v_mfma_f32_16x16x32_bf16 v[8:11], v[32:35], v[44:47], v[20:23]
	s_waitcnt lgkmcnt(2)
	v_mfma_f32_16x16x32_bf16 v[12:15], v[48:51], v[44:47], v[36:39]
	s_waitcnt lgkmcnt(1)
	v_mfma_f32_16x16x32_bf16 v[16:19], v[52:55], v[44:47], v[40:43]
	s_waitcnt lgkmcnt(0)
	v_mfma_f32_16x16x32_bf16 v[20:23], v[64:67], v[44:47], v[24:27]
	s_andn2_b64 vcc, exec, s[74:75]
	s_mov_b64 s[68:69], -1
	s_cbranch_vccnz .LBB0_298
; __device__ __forceinline__ unsigned cvt_pk_bf16(float lo, float hi) { const f32x2 v = (f32x2){lo, hi}; return __builtin_bit_cast(unsigned, __builtin_convertvector(v, bf16v2)); }
; __device__ __forceinline__ void attn_store(bf16_t* MIX, int qtok, int h, int g, float lsum, const f32x4 (&o)[4]) {
;     lsum += __shfl_xor(lsum, 16); lsum += __shfl_xor(lsum, 32);
;     const float inv = 1.f / lsum;
;     bf16_t* op = MIX + (size_t)qtok * DM + 512 + h * 64 + 4 * g;
; #pragma unroll
;     for (int dt = 0; dt < 4; ++dt) { u32x2 w; w.x = cvt_pk_bf16(o[dt][0] * inv, o[dt][1] * inv); w.y = cvt_pk_bf16(o[dt][2] * inv, o[dt][3] * inv); *(u32x2*)(op + 16 * dt) = w; }
; }
	ds_bpermute_b32 v24, v114, v28
	v_ashrrev_i32_e32 v105, 31, v104
	s_waitcnt lgkmcnt(0)
	v_add_f32_e32 v24, v28, v24
	ds_bpermute_b32 v25, v115, v24
	s_waitcnt lgkmcnt(0)
	v_add_f32_e32 v24, v24, v25
	v_div_scale_f32 v25, s[68:69], v24, v24, 1.0
	v_rcp_f32_e32 v26, v25
	s_mov_b64 s[68:69], 0
	v_fma_f32 v27, -v25, v26, 1.0
	v_fmac_f32_e32 v26, v27, v26
	v_div_scale_f32 v27, vcc, 1.0, v24, 1.0
	v_mul_f32_e32 v29, v27, v26
	v_fma_f32 v30, -v25, v29, v27
	v_fmac_f32_e32 v29, v30, v26
	v_fma_f32 v25, -v25, v29, v27
	v_div_fmas_f32 v25, v25, v26, v29
	v_div_fixup_f32 v24, v25, v24, 1.0
	v_lshlrev_b64 v[26:27], 11, v[104:105]
	v_pk_mul_f32 v[30:31], v[8:9], v[24:25] op_sel_hi:[1,0]
	v_pk_mul_f32 v[32:33], v[10:11], v[24:25] op_sel_hi:[1,0]
	v_lshl_add_u64 v[26:27], v[102:103], 0, v[26:27]
	v_cvt_pk_bf16_f32 v30, v30, v31
	v_cvt_pk_bf16_f32 v31, v32, v33
	global_store_dwordx2 v[26:27], v[30:31], off offset:1024
	v_pk_mul_f32 v[30:31], v[12:13], v[24:25] op_sel_hi:[1,0]
	v_pk_mul_f32 v[32:33], v[14:15], v[24:25] op_sel_hi:[1,0]
	v_cvt_pk_bf16_f32 v30, v30, v31
	v_cvt_pk_bf16_f32 v31, v32, v33
	global_store_dwordx2 v[26:27], v[30:31], off offset:1056
	v_pk_mul_f32 v[30:31], v[16:17], v[24:25] op_sel_hi:[1,0]
	v_pk_mul_f32 v[32:33], v[18:19], v[24:25] op_sel_hi:[1,0]
	v_cvt_pk_bf16_f32 v30, v30, v31
	v_cvt_pk_bf16_f32 v31, v32, v33
	global_store_dwordx2 v[26:27], v[30:31], off offset:1088
	v_pk_mul_f32 v[30:31], v[20:21], v[24:25] op_sel_hi:[1,0]
	v_pk_mul_f32 v[24:25], v[22:23], v[24:25] op_sel_hi:[1,0]
	v_cvt_pk_bf16_f32 v30, v30, v31
	v_cvt_pk_bf16_f32 v31, v24, v25
	global_store_dwordx2 v[26:27], v[30:31], off offset:1120
	s_branch .LBB0_298
